# v56 + beta/decay gate math of the GDN chunk-local unit moved from step 2 to the unit start on the wave that has no conv work
# speedup vs baseline: 1.0020x; 1.0020x over previous
; __device__ __forceinline__ void gdn_local_unit(LAS unsigned char* lds, const GdnP& P, int unit, const int tid, const int pf) {
;     ...
;     else if (tid < 192) { const int t = tid - 128; const float bl = P.baf[(size_t)(row0 + t) * 16 + h], al = P.baf[(size_t)(row0 + t) * 16 + 8 + h];
;         beta[t] = 1.f / (1.f + expf(-bl)); const float x = al + P.dt_bias[h]; const float sp = x > 20.f ? x : log1pf(expf(x)); gb[t] = -expf(P.a_log[h]) * sp; }
.LBB0_751:
	v_mov_b32_e32 v132, v101
	v_mov_b32_e32 v131, v208
	v_mov_b32_e32 v219, v209
	v_mov_b32_e32 v109, v210
	v_mov_b32_e32 v130, v211
	s_waitcnt lgkmcnt(0)
	s_barrier
	s_ashr_i32 s3, s80, 3
	v_readfirstlane_b32 s2, v165
	s_and_b32 s93, s80, 7
	s_lshl_b32 s92, s3, 6
	v_lshrrev_b32_e32 v16, 6, v165
	v_cmp_eq_u32_e64 s[64:65], 6, v16
	s_and_saveexec_b64 s[62:63], s[64:65]
	s_cbranch_execz .Lge_done
	v_add_u32_e32 v0, s92, v103
	s_waitcnt lgkmcnt(0)
	v_ashrrev_i32_e32 v1, 31, v0
	v_lshlrev_b64 v[0:1], 6, v[0:1]
	v_lshl_add_u64 v[0:1], s[72:73], 0, v[0:1]
	s_lshl_b32 s58, s93, 2
	v_lshl_add_u64 v[0:1], v[0:1], 0, s[58:59]
	global_load_dword v2, v[0:1], off
	s_nop 0
	global_load_dword v1, v[0:1], off offset:32
	v_mov_b32_e32 v243, s58
	global_load_dword v244, v243, s[74:75]
	global_load_dword v245, v243, s[46:47]
	s_mov_b32 s54, 0xbfb8aa3b
	s_waitcnt vmcnt(1)
	v_mul_f32_e32 v0, 0xbfb8aa3b, v2
	v_fma_f32 v3, v2, s54, -v0
	v_rndne_f32_e32 v4, v0
	v_fmac_f32_e32 v3, 0xb2a5705f, v2
	v_sub_f32_e32 v0, v0, v4
	v_add_f32_e32 v0, v0, v3
	v_exp_f32_e32 v0, v0
	v_cvt_i32_f32_e32 v3, v4
	s_mov_b32 s54, 0x42ce8ed0
	v_cmp_nlt_f32_e32 vcc, s54, v2
	s_mov_b32 s54, 0xc2b17218
	v_ldexp_f32 v0, v0, v3
	v_cndmask_b32_e32 v0, 0, v0, vcc
	v_cmp_ngt_f32_e32 vcc, s54, v2
	s_mov_b32 s54, 0x41a00000
	s_nop 0
	v_cndmask_b32_e32 v0, v214, v0, vcc
	v_add_f32_e32 v0, 1.0, v0
	v_div_scale_f32 v2, s[42:43], v0, v0, 1.0
	v_rcp_f32_e32 v3, v2
	s_nop 0
	v_fma_f32 v4, -v2, v3, 1.0
	v_fmac_f32_e32 v3, v4, v3
	v_div_scale_f32 v4, vcc, 1.0, v0, 1.0
	v_mul_f32_e32 v5, v4, v3
	v_fma_f32 v6, -v2, v5, v4
	v_fmac_f32_e32 v5, v6, v3
	v_fma_f32 v2, -v2, v5, v4
	v_div_fmas_f32 v2, v2, v3, v5
	v_div_fixup_f32 v2, v2, v0, 1.0
	v_lshl_add_u32 v0, v103, 2, v130
	v_add_u32_e32 v0, 0x200, v0
	ds_write_b32 v0, v2
	s_waitcnt vmcnt(0)
	v_mov_b32_e32 v2, v244
	v_add_f32_e32 v1, v1, v2
	v_cmp_nlt_f32_e32 vcc, s54, v1
	s_and_saveexec_b64 s[42:43], vcc
	s_cbranch_execz .Lge_892
	v_mul_f32_e32 v2, 0x3fb8aa3b, v1
	v_rndne_f32_e32 v3, v2
	v_sub_f32_e32 v4, v2, v3
	v_fma_f32 v2, v1, s88, -v2
	v_fmac_f32_e32 v2, 0x32a5705f, v1
	v_add_f32_e32 v2, v4, v2
	v_cvt_i32_f32_e32 v3, v3
	v_exp_f32_e32 v2, v2
	v_cmp_ngt_f32_e32 vcc, s89, v1
	s_mov_b32 s54, 0x3f2aaaab
	v_ldexp_f32 v2, v2, v3
	v_cndmask_b32_e32 v2, 0, v2, vcc
	v_cmp_nlt_f32_e32 vcc, s90, v1
	s_nop 1
	v_cndmask_b32_e32 v1, v214, v2, vcc
	v_add_f32_e32 v4, 1.0, v1
	v_add_f32_e32 v2, -1.0, v4
	v_sub_f32_e32 v3, v2, v4
	v_add_f32_e32 v3, 1.0, v3
	v_sub_f32_e32 v2, v1, v2
	v_add_f32_e32 v5, v2, v3
	v_frexp_mant_f32_e32 v6, v4
	v_cvt_f64_f32_e32 v[2:3], v4
	v_frexp_exp_i32_f64_e32 v2, v[2:3]
	v_cmp_gt_f32_e32 vcc, s54, v6
	s_mov_b32 s54, 0x3f317218
	s_nop 0
	v_subbrev_co_u32_e32 v10, vcc, 0, v2, vcc
	v_sub_u32_e32 v2, 0, v10
	v_ldexp_f32 v3, v4, v2
	v_add_f32_e32 v4, -1.0, v3
	v_add_f32_e32 v6, 1.0, v3
	v_ldexp_f32 v2, v5, v2
	v_add_f32_e32 v5, 1.0, v4
	v_add_f32_e32 v7, -1.0, v6
	v_sub_f32_e32 v5, v3, v5
	v_sub_f32_e32 v3, v3, v7
	v_add_f32_e32 v5, v2, v5
	v_add_f32_e32 v2, v2, v3
	v_add_f32_e32 v11, v6, v2
	v_rcp_f32_e32 v13, v11
	v_sub_f32_e32 v3, v6, v11
	v_add_f32_e32 v12, v2, v3
	v_add_f32_e32 v3, v4, v5
	v_mul_f32_e32 v15, v3, v13
	v_sub_f32_e32 v2, v4, v3
	v_mul_f32_e32 v4, v11, v15
	v_fma_f32 v6, v15, v11, -v4
	v_fmac_f32_e32 v6, v15, v12
	v_add_f32_e32 v14, v5, v2
	v_add_f32_e32 v2, v4, v6
	v_sub_f32_e32 v5, v3, v2
	v_pk_add_f32 v[8:9], v[2:3], v[4:5] neg_lo:[0,1] neg_hi:[0,1]
	v_mov_b32_e32 v7, v2
	v_pk_add_f32 v[2:3], v[8:9], v[6:7] neg_lo:[0,1] neg_hi:[0,1]
	s_nop 0
	v_add_f32_e32 v3, v14, v3
	v_add_f32_e32 v2, v2, v3
	v_add_f32_e32 v3, v5, v2
	v_mul_f32_e32 v14, v13, v3
	v_mul_f32_e32 v4, v11, v14
	v_fma_f32 v6, v14, v11, -v4
	v_fmac_f32_e32 v6, v14, v12
	v_sub_f32_e32 v5, v5, v3
	v_add_f32_e32 v11, v2, v5
	v_add_f32_e32 v2, v4, v6
	v_sub_f32_e32 v5, v3, v2
	v_pk_add_f32 v[8:9], v[2:3], v[4:5] neg_lo:[0,1] neg_hi:[0,1]
	v_mov_b32_e32 v7, v2
	v_pk_add_f32 v[2:3], v[8:9], v[6:7] neg_lo:[0,1] neg_hi:[0,1]
	s_nop 0
	v_add_f32_e32 v3, v11, v3
	v_add_f32_e32 v2, v2, v3
	v_add_f32_e32 v3, v15, v14
	v_add_f32_e32 v2, v5, v2
	v_sub_f32_e32 v4, v3, v15
	v_mul_f32_e32 v2, v13, v2
	v_sub_f32_e32 v4, v14, v4
	v_add_f32_e32 v4, v4, v2
	v_add_f32_e32 v6, v3, v4
	v_mul_f32_e32 v7, v6, v6
	v_fmamk_f32 v2, v7, 0x3e9b6dac, v212
	v_fmaak_f32 v111, v7, v2, 0x3f2aaada
	v_cvt_f32_i32_e32 v2, v10
	v_sub_f32_e32 v3, v6, v3
	v_sub_f32_e32 v3, v4, v3
	v_ldexp_f32 v8, v3, 1
	v_mul_f32_e32 v3, v6, v7
	v_ldexp_f32 v5, v6, 1
	v_pk_mul_f32 v[6:7], v[2:3], v[110:111]
	s_nop 0
	v_fma_f32 v4, v2, s54, -v6
	v_fmac_f32_e32 v4, 0xb102e308, v2
	v_pk_add_f32 v[2:3], v[6:7], v[4:5]
	s_mov_b32 s54, 0x7f800000
	v_sub_f32_e32 v5, v3, v5
	v_sub_f32_e32 v5, v7, v5
	v_add_f32_e32 v9, v8, v5
	v_mov_b32_e32 v8, v6
	v_pk_add_f32 v[6:7], v[2:3], v[6:7] neg_lo:[0,1] neg_hi:[0,1]
	v_pk_add_f32 v[10:11], v[2:3], v[8:9]
	v_mov_b32_e32 v5, v2
	v_mov_b32_e32 v7, v11
	v_pk_add_f32 v[12:13], v[4:5], v[6:7] neg_lo:[0,1] neg_hi:[0,1]
	v_pk_add_f32 v[4:5], v[4:5], v[6:7]
	v_mov_b32_e32 v8, v9
	v_pk_add_f32 v[6:7], v[4:5], v[2:3] op_sel:[1,0] op_sel_hi:[0,1] neg_lo:[0,1] neg_hi:[0,1]
	v_pk_add_f32 v[14:15], v[10:11], v[6:7] op_sel_hi:[1,0] neg_lo:[0,1] neg_hi:[0,1]
	v_mov_b32_e32 v10, v11
	v_mov_b32_e32 v11, v5
	v_pk_mov_b32 v[6:7], v[2:3], v[6:7] op_sel:[1,0]
	v_mov_b32_e32 v9, v2
	v_pk_add_f32 v[6:7], v[10:11], v[6:7] neg_lo:[0,1] neg_hi:[0,1]
	v_mov_b32_e32 v14, v12
	v_pk_add_f32 v[2:3], v[8:9], v[6:7] neg_lo:[0,1] neg_hi:[0,1]
	v_mov_b32_e32 v13, v5
	v_pk_add_f32 v[6:7], v[14:15], v[2:3]
	v_cmp_neq_f32_e32 vcc, s54, v1
	v_pk_add_f32 v[8:9], v[6:7], v[6:7] op_sel:[0,1] op_sel_hi:[1,0]
	s_mov_b32 s54, 0x33800000
	v_pk_add_f32 v[4:5], v[4:5], v[8:9] op_sel:[1,0] op_sel_hi:[0,1]
	v_mov_b32_e32 v7, v4
	v_pk_add_f32 v[10:11], v[6:7], v[12:13] neg_lo:[0,1] neg_hi:[0,1]
	v_mov_b32_e32 v3, v8
	v_sub_f32_e32 v5, v6, v10
	v_pk_add_f32 v[2:3], v[2:3], v[10:11] neg_lo:[0,1] neg_hi:[0,1]
	v_sub_f32_e32 v5, v12, v5
	v_add_f32_e32 v2, v2, v5
	v_add_f32_e32 v2, v2, v3
	v_add_f32_e32 v2, v4, v2
	v_cndmask_b32_e32 v2, v214, v2, vcc
	v_cmp_lt_f32_e64 vcc, |v1|, s54
	s_nop 1
	v_cndmask_b32_e32 v1, v2, v1, vcc

; __device__ __forceinline__ void gdn_local_unit(LAS unsigned char* lds, const GdnP& P, int unit, const int tid, const int pf) {
;     ...
;     if (tid < 384 && !(pf & 32)) {
;         const int c8 = tid & 15, which = (tid >> 4) % 3, tseg = tid / 48, t0 = tseg * 8, col = which * 1024 + h * 128 + c8 * 8;
;         float wg[4][8];
; #pragma unroll
;         for (int i = 0; i < 4; ++i) { const f32x4 w0 = *(const f32x4*)(P.conv + i * 3072 + col), w1 = *(const f32x4*)(P.conv + i * 3072 + col + 4);
;             wg[i][0] = w0.x; wg[i][1] = w0.y; wg[i][2] = w0.z; wg[i][3] = w0.w; wg[i][4] = w1.x; wg[i][5] = w1.y; wg[i][6] = w1.z; wg[i][7] = w1.w; }
;         u32x4 raw[11];
; #pragma unroll
;         for (int r = 0; r < 11; ++r) { const int tt = t0 - 3 + r; raw[r] = (u32x4){0u, 0u, 0u, 0u};
;             if (tt >= 0) raw[r] = *(const u32x4*)(P.proj + (size_t)(row0 + tt) * NIN + C_GDN + col);
;             else if (n > 0) raw[r] = *(const u32x4*)(P.halo + ((size_t)(cn - 1) * 3 + (tt + 3)) * 3072 + col); }
.Lge_done:
	s_or_b64 exec, exec, s[62:63]
	s_and_saveexec_b64 s[0:1], s[76:77]
	s_cbranch_execz .LBB0_888
	v_lshl_or_b32 v112, s93, 7, v99
	v_ashrrev_i32_e32 v113, 31, v112
	v_lshl_add_u64 v[12:13], v[112:113], 2, s[44:45]
	v_add_co_u32_e32 v6, vcc, 0x3000, v12
	s_mov_b64 s[40:41], 0x3000
	s_nop 0
	v_addc_co_u32_e32 v7, vcc, 0, v13, vcc
	v_lshl_add_u64 v[4:5], v[12:13], 0, s[40:41]
	s_mov_b64 s[40:41], 0x6000
	v_add_co_u32_e32 v10, vcc, 0x6000, v12
	v_lshl_add_u64 v[8:9], v[12:13], 0, s[40:41]
	s_nop 0
	v_addc_co_u32_e32 v11, vcc, 0, v13, vcc
	s_mov_b64 s[40:41], 0x9000
	s_waitcnt lgkmcnt(0)
	global_load_dwordx4 v[0:3], v[12:13], off offset:16
	global_load_dwordx4 v[16:19], v[12:13], off
	v_lshl_add_u64 v[14:15], v[12:13], 0, s[40:41]
	v_add_co_u32_e32 v12, vcc, 0x9000, v12
	global_load_dwordx4 v[20:23], v[6:7], off
	s_nop 0
	global_load_dwordx4 v[4:7], v[4:5], off offset:16
	v_addc_co_u32_e32 v13, vcc, 0, v13, vcc
	global_load_dwordx4 v[24:27], v[10:11], off
	s_nop 0
	global_load_dwordx4 v[8:11], v[8:9], off offset:16
	s_nop 0
	global_load_dwordx4 v[28:31], v[12:13], off
	s_nop 0
	global_load_dwordx4 v[12:15], v[14:15], off offset:16
	s_and_b32 s33, s80, 0x1f8
	s_cmp_lg_u32 s33, 0
	s_cselect_b64 s[40:41], -1, 0
	s_mul_i32 s3, s3, 3
	s_add_i32 s42, s3, -3
	v_cndmask_b32_e64 v34, 0, 1, s[40:41]
	s_ashr_i32 s43, s42, 31
	v_lshl_add_u64 v[32:33], v[112:113], 1, s[70:71]
	v_cmp_ne_u32_e64 s[40:41], 1, v34
	s_and_saveexec_b64 s[52:53], s[4:5]
	s_xor_b64 s[52:53], exec, s[52:53]
	s_cbranch_execz .LBB0_755
	s_and_b64 vcc, exec, s[40:41]
	s_cbranch_vccnz .LBB0_1033
	v_lshl_add_u64 v[34:35], s[42:43], 0, v[76:77]
	v_mad_u64_u32 v[36:37], s[60:61], v34, s86, v[32:33]
	v_mad_i32_i24 v37, v35, s86, v37
	global_load_dwordx4 v[56:59], v[36:37], off
	s_andn2_saveexec_b64 s[52:53], s[52:53]
	s_cbranch_execz .LBB0_757
	s_branch .LBB0_756

; __device__ __forceinline__ void gdn_local_unit(LAS unsigned char* lds, const GdnP& P, int unit, const int tid, const int pf) {
;     ...
;     else if (tid < 192) { const int t = tid - 128; const float bl = P.baf[(size_t)(row0 + t) * 16 + h], al = P.baf[(size_t)(row0 + t) * 16 + 8 + h];
;         beta[t] = 1.f / (1.f + expf(-bl)); const float x = al + P.dt_bias[h]; const float sp = x > 20.f ? x : log1pf(expf(x)); gb[t] = -expf(P.a_log[h]) * sp; }
.LBB0_888:
	s_or_b64 exec, exec, s[0:1]
	s_waitcnt lgkmcnt(0)
	s_barrier
	s_and_saveexec_b64 s[0:1], s[8:9]
	s_xor_b64 s[0:1], exec, s[0:1]
	s_cbranch_execz .LBB0_894
	s_and_saveexec_b64 s[40:41], s[10:11]
	s_branch .LBB0_893
